# nt hint on the row loads of all five norm phases (on v67)
# speedup vs baseline: 1.0208x; 1.0019x over previous
; __device__ __forceinline__ void norm_mod_bf16_phase(const Ctx& F, const bf16_t* xin, const float* gain, const float* shift, const float* scale) {
;     ...
;         for (int r = 0; r < 32; r += 4) {
;             u32x4 raw[4][2]; float s[4];
; #pragma unroll
;             for (int u = 0; u < 4; ++u)
; #pragma unroll
;                 for (int j = 0; j < 2; ++j) raw[u][j] = *(const u32x4*)(xin + (size_t)(row0 + r + u) * D + 8 * ln + 512 * j);
; #pragma unroll
;             for (int u = 0; u < 4; ++u) { s[u] = 0.f;
; #pragma unroll
;                 for (int j = 0; j < 2; ++j) { float f[8]; unpack8(raw[u][j], f);
; #pragma unroll
;                     for (int e = 0; e < 8; ++e) s[u] += f[e] * f[e]; }
.LBB0_984:
	v_lshl_add_u64 v[40:41], s[28:29], 0, v[22:23]
	v_lshl_add_u64 v[42:43], s[36:37], 0, v[22:23]
	v_lshl_add_u64 v[44:45], s[56:57], 0, v[22:23]
	v_lshl_add_u64 v[46:47], s[34:35], 0, v[22:23]
	global_load_dwordx4 v[60:63], v[40:41], off nt
	global_load_dwordx4 v[68:71], v[42:43], off nt
	global_load_dwordx4 v[72:75], v[44:45], off nt
	global_load_dwordx4 v[116:119], v[46:47], off offset:1024 nt
	global_load_dwordx4 v[84:87], v[40:41], off offset:-1024 nt
	global_load_dwordx4 v[88:91], v[42:43], off offset:-1024 nt
	global_load_dwordx4 v[120:123], v[44:45], off offset:-1024 nt
	global_load_dwordx4 v[124:127], v[46:47], off nt
	v_lshl_add_u64 v[48:49], s[26:27], 0, v[22:23]
	v_add_co_u32_e32 v46, vcc, s48, v48
	v_lshl_add_u64 v[50:51], s[30:31], 0, v[22:23]
	s_nop 0
	v_addc_co_u32_e32 v47, vcc, 0, v49, vcc
	v_add_co_u32_e32 v44, vcc, s48, v50
	v_lshl_add_u64 v[52:53], s[38:39], 0, v[22:23]
	s_nop 0
	v_addc_co_u32_e32 v45, vcc, 0, v51, vcc
	v_add_co_u32_e32 v42, vcc, s48, v52
	v_lshl_add_u64 v[54:55], s[40:41], 0, v[22:23]
	s_nop 0
	v_addc_co_u32_e32 v43, vcc, 0, v53, vcc
	v_add_co_u32_e32 v40, vcc, s48, v54
	s_add_u32 s26, s26, 0x2000
	s_nop 0
	v_addc_co_u32_e32 v41, vcc, 0, v55, vcc
	s_addc_u32 s27, s27, 0
	s_add_i32 s19, s19, 4
	s_add_u32 s28, s28, 0x2000
	s_addc_u32 s29, s29, 0
	s_add_u32 s30, s30, 0x2000
	s_addc_u32 s31, s31, 0
	s_add_u32 s34, s34, 0x2000
	s_addc_u32 s35, s35, 0
	s_add_u32 s36, s36, 0x2000
	s_addc_u32 s37, s37, 0
	s_add_u32 s38, s38, 0x2000
	s_addc_u32 s39, s39, 0
	s_add_u32 s40, s40, 0x2000
	s_addc_u32 s41, s41, 0
	s_add_u32 s56, s56, 0x2000
	s_addc_u32 s57, s57, 0
	s_cmp_gt_u32 s19, 27
	s_waitcnt vmcnt(7)
	v_and_b32_e32 v80, 0xffff0000, v62
	s_waitcnt vmcnt(6)
	v_and_b32_e32 v64, 0xffff0000, v69
	s_waitcnt vmcnt(5)
	v_and_b32_e32 v56, 0xffff0000, v74
	v_lshlrev_b32_e32 v57, 16, v74
	s_waitcnt vmcnt(3)
	v_lshlrev_b32_e32 v110, 16, v84
	v_and_b32_e32 v111, 0xffff0000, v84
	v_lshlrev_b32_e32 v106, 16, v85
	v_and_b32_e32 v107, 0xffff0000, v85
	s_waitcnt vmcnt(2)
	v_lshlrev_b32_e32 v92, 16, v91
	v_and_b32_e32 v93, 0xffff0000, v91
	v_lshlrev_b32_e32 v94, 16, v90
	v_and_b32_e32 v95, 0xffff0000, v90
	v_lshlrev_b32_e32 v100, 16, v88
	v_and_b32_e32 v101, 0xffff0000, v88
	s_waitcnt vmcnt(1)
	v_lshlrev_b32_e32 v90, 16, v120
	v_and_b32_e32 v91, 0xffff0000, v120
	v_pk_mul_f32 v[146:147], v[110:111], v[110:111]
	v_and_b32_e32 v58, 0xffff0000, v75
	v_lshlrev_b32_e32 v59, 16, v75
	v_lshlrev_b32_e32 v102, 16, v87
	v_and_b32_e32 v103, 0xffff0000, v87
	v_lshlrev_b32_e32 v104, 16, v86
	v_and_b32_e32 v105, 0xffff0000, v86
	v_lshlrev_b32_e32 v96, 16, v89
	v_and_b32_e32 v97, 0xffff0000, v89
	v_lshlrev_b32_e32 v86, 16, v121
	v_and_b32_e32 v87, 0xffff0000, v121
	s_waitcnt vmcnt(0)
	v_lshlrev_b32_e32 v74, 16, v124
	v_and_b32_e32 v75, 0xffff0000, v124
	v_pk_mul_f32 v[144:145], v[106:107], v[106:107]
	v_pk_mul_f32 v[156:157], v[100:101], v[100:101]
	v_pk_mul_f32 v[166:167], v[90:91], v[90:91]
	v_add_f32_e32 v115, v146, v147
	v_lshlrev_b32_e32 v65, 16, v69
	v_lshlrev_b32_e32 v98, 16, v68
	v_and_b32_e32 v99, 0xffff0000, v68
	v_lshlrev_b32_e32 v68, 16, v125
	v_and_b32_e32 v69, 0xffff0000, v125
	v_pk_mul_f32 v[154:155], v[96:97], v[96:97]
	v_pk_mul_f32 v[164:165], v[86:87], v[86:87]
	v_pk_mul_f32 v[176:177], v[74:75], v[74:75]
	v_add_f32_e32 v146, v156, v157
	v_add_f32_e32 v147, v166, v167
	v_add_f32_e32 v115, v144, v115
	v_lshlrev_b32_e32 v84, 16, v122
	v_and_b32_e32 v85, 0xffff0000, v122
	v_pk_mul_f32 v[142:143], v[104:105], v[104:105]
	v_pk_mul_f32 v[174:175], v[68:69], v[68:69]
	v_add_f32_e32 v156, v176, v177
	v_add_f32_e32 v144, v154, v146
	v_add_f32_e32 v146, v164, v147
	v_add_f32_e32 v115, v145, v115
	v_lshlrev_b32_e32 v81, 16, v62
	v_and_b32_e32 v82, 0xffff0000, v63
	v_lshlrev_b32_e32 v83, 16, v63
	v_lshlrev_b32_e32 v62, 16, v126
	v_and_b32_e32 v63, 0xffff0000, v126
	v_pk_mul_f32 v[152:153], v[94:95], v[94:95]
	v_pk_mul_f32 v[162:163], v[84:85], v[84:85]
	v_add_f32_e32 v147, v174, v156
	v_add_f32_e32 v144, v155, v144
	v_add_f32_e32 v145, v165, v146
	v_add_f32_e32 v115, v142, v115
	v_lshlrev_b32_e32 v76, 16, v123
	v_and_b32_e32 v77, 0xffff0000, v123
	v_pk_mul_f32 v[140:141], v[102:103], v[102:103]
	v_pk_mul_f32 v[172:173], v[62:63], v[62:63]
	v_add_f32_e32 v146, v175, v147
	v_add_f32_e32 v142, v152, v144
	v_add_f32_e32 v144, v162, v145
	v_add_f32_e32 v115, v143, v115
	v_and_b32_e32 v78, 0xffff0000, v61
	v_lshlrev_b32_e32 v79, 16, v61
	v_lshlrev_b32_e32 v108, 16, v60
	v_and_b32_e32 v109, 0xffff0000, v60
	v_lshlrev_b32_e32 v60, 16, v127
	v_and_b32_e32 v61, 0xffff0000, v127
	v_pk_mul_f32 v[150:151], v[92:93], v[92:93]
	v_pk_mul_f32 v[160:161], v[76:77], v[76:77]
	v_add_f32_e32 v145, v172, v146
	v_add_f32_e32 v142, v153, v142
	v_add_f32_e32 v143, v163, v144
	v_add_f32_e32 v115, v140, v115
	v_lshlrev_b32_e32 v88, 16, v72
	v_and_b32_e32 v89, 0xffff0000, v72
	v_pk_mul_f32 v[148:149], v[108:109], v[108:109]
	v_pk_mul_f32 v[170:171], v[60:61], v[60:61]
	v_add_f32_e32 v144, v173, v145
	v_add_f32_e32 v140, v150, v142
	v_add_f32_e32 v142, v160, v143
	v_add_f32_e32 v115, v141, v115
	v_and_b32_e32 v54, 0xffff0000, v73
	v_lshlrev_b32_e32 v55, 16, v73
	v_lshlrev_b32_e32 v72, 16, v116
	v_and_b32_e32 v73, 0xffff0000, v116
	v_pk_mul_f32 v[158:159], v[98:99], v[98:99]
	v_pk_mul_f32 v[168:169], v[88:89], v[88:89]
	v_add_f32_e32 v143, v170, v144
	v_add_f32_e32 v140, v151, v140
	v_add_f32_e32 v141, v161, v142
	v_add_f32_e32 v115, v148, v115
	v_and_b32_e32 v48, 0xffff0000, v117
	v_lshlrev_b32_e32 v49, 16, v117
	v_pk_mul_f32 v[116:117], v[78:79], v[78:79]
	v_pk_mul_f32 v[178:179], v[72:73], v[72:73]
	v_add_f32_e32 v142, v171, v143
	v_add_f32_e32 v140, v158, v140
; __device__ __forceinline__ float wave_sum_fast(float x) { x = reduce16(x); return (rl_(x, 0) + rl_(x, 16)) + (rl_(x, 32) + rl_(x, 48)); }
; __device__ __forceinline__ void norm_mod_bf16_phase(const Ctx& F, const bf16_t* xin, const float* gain, const float* shift, const float* scale) {
;     ...
;             for (int u = 0; u < 4; ++u) { s[u] = 0.f;
; #pragma unroll
;                 for (int j = 0; j < 2; ++j) { float f[8]; unpack8(raw[u][j], f);
; #pragma unroll
;                     for (int e = 0; e < 8; ++e) s[u] += f[e] * f[e]; }
;                 s[u] = wave_sum_fast(s[u]); }
; #pragma unroll
;             for (int u = 0; u < 4; ++u) { const float rstd = 1.0f / sqrtf(s[u] * (1.0f / D) + 1e-6f);
	v_add_f32_e32 v141, v168, v141
	v_add_f32_e32 v115, v149, v115
	v_pk_mul_f32 v[122:123], v[64:65], v[64:65]
	v_pk_mul_f32 v[128:129], v[54:55], v[54:55]
	v_add_f32_e32 v142, v178, v142
	v_add_f32_e32 v140, v159, v140
	v_add_f32_e32 v141, v169, v141
	v_add_f32_e32 v115, v117, v115
	v_and_b32_e32 v66, 0xffff0000, v70
	v_lshlrev_b32_e32 v67, 16, v70
	v_and_b32_e32 v50, 0xffff0000, v118
	v_lshlrev_b32_e32 v51, 16, v118
	v_and_b32_e32 v52, 0xffff0000, v119
	v_lshlrev_b32_e32 v53, 16, v119
	v_pk_mul_f32 v[118:119], v[80:81], v[80:81]
	v_pk_mul_f32 v[134:135], v[48:49], v[48:49]
	v_add_f32_e32 v142, v179, v142
	v_add_f32_e32 v117, v123, v140
	v_add_f32_e32 v123, v129, v141
	v_add_f32_e32 v115, v116, v115
	v_pk_mul_f32 v[124:125], v[66:67], v[66:67]
	v_pk_mul_f32 v[130:131], v[56:57], v[56:57]
	v_add_f32_e32 v129, v135, v142
	v_add_f32_e32 v116, v122, v117
	v_add_f32_e32 v117, v128, v123
	v_add_f32_e32 v115, v119, v115
	v_and_b32_e32 v70, 0xffff0000, v71
	v_lshlrev_b32_e32 v71, 16, v71
	v_pk_mul_f32 v[120:121], v[82:83], v[82:83]
	v_pk_mul_f32 v[136:137], v[50:51], v[50:51]
	v_add_f32_e32 v122, v134, v129
	v_add_f32_e32 v116, v125, v116
	v_add_f32_e32 v117, v131, v117
	v_add_f32_e32 v115, v118, v115
	v_pk_mul_f32 v[126:127], v[70:71], v[70:71]
	v_pk_mul_f32 v[132:133], v[58:59], v[58:59]
	v_add_f32_e32 v119, v137, v122
	v_add_f32_e32 v116, v124, v116
	v_add_f32_e32 v117, v130, v117
	v_add_f32_e32 v115, v121, v115
	v_pk_mul_f32 v[138:139], v[52:53], v[52:53]
	v_add_f32_e32 v118, v136, v119
	v_add_f32_e32 v116, v127, v116
	v_add_f32_e32 v117, v133, v117
	v_add_f32_e32 v115, v120, v115
	v_add_f32_e32 v118, v139, v118
	v_add_f32_e32 v116, v126, v116
	v_add_f32_e32 v117, v132, v117
	v_add_f32_dpp v115, v115, v115 quad_perm:[1,0,3,2] row_mask:0xf bank_mask:0xf bound_ctrl:1
	v_add_f32_e32 v118, v138, v118
	v_add_f32_dpp v116, v116, v116 quad_perm:[1,0,3,2] row_mask:0xf bank_mask:0xf bound_ctrl:1
	v_add_f32_dpp v117, v117, v117 quad_perm:[1,0,3,2] row_mask:0xf bank_mask:0xf bound_ctrl:1
	v_add_f32_dpp v115, v115, v115 quad_perm:[2,3,0,1] row_mask:0xf bank_mask:0xf bound_ctrl:1
	v_add_f32_dpp v118, v118, v118 quad_perm:[1,0,3,2] row_mask:0xf bank_mask:0xf bound_ctrl:1
	v_add_f32_dpp v116, v116, v116 quad_perm:[2,3,0,1] row_mask:0xf bank_mask:0xf bound_ctrl:1
	v_add_f32_dpp v117, v117, v117 quad_perm:[2,3,0,1] row_mask:0xf bank_mask:0xf bound_ctrl:1
	v_add_f32_dpp v115, v115, v115 row_half_mirror row_mask:0xf bank_mask:0xf bound_ctrl:1
	v_add_f32_dpp v118, v118, v118 quad_perm:[2,3,0,1] row_mask:0xf bank_mask:0xf bound_ctrl:1
	v_add_f32_dpp v116, v116, v116 row_half_mirror row_mask:0xf bank_mask:0xf bound_ctrl:1
	v_add_f32_dpp v117, v117, v117 row_half_mirror row_mask:0xf bank_mask:0xf bound_ctrl:1
	v_add_f32_dpp v115, v115, v115 row_mirror row_mask:0xf bank_mask:0xf bound_ctrl:1
	v_add_f32_dpp v118, v118, v118 row_half_mirror row_mask:0xf bank_mask:0xf bound_ctrl:1
	v_add_f32_dpp v116, v116, v116 row_mirror row_mask:0xf bank_mask:0xf bound_ctrl:1
	v_add_f32_dpp v117, v117, v117 row_mirror row_mask:0xf bank_mask:0xf bound_ctrl:1
	v_readlane_b32 s12, v115, 16
	v_readlane_b32 s13, v115, 48
	v_add_f32_dpp v118, v118, v118 row_mirror row_mask:0xf bank_mask:0xf bound_ctrl:1
	v_readlane_b32 s4, v115, 0
	v_readlane_b32 s5, v115, 32
	v_readlane_b32 s6, v116, 0
	v_readlane_b32 s14, v116, 16
	v_readlane_b32 s7, v116, 32
	v_readlane_b32 s15, v116, 48
	v_readlane_b32 s8, v117, 0
	v_readlane_b32 s16, v117, 16
	v_readlane_b32 s9, v117, 32
	v_readlane_b32 s17, v117, 48
	v_mov_b32_e32 v116, s12
	v_mov_b32_e32 v117, s13
	v_readlane_b32 s10, v118, 0
	v_readlane_b32 s21, v118, 16
	v_readlane_b32 s11, v118, 32
	v_readlane_b32 s23, v118, 48
	v_mov_b32_e32 v118, s14
	v_mov_b32_e32 v119, s15
	v_mov_b32_e32 v120, s16
	v_mov_b32_e32 v121, s17
	v_pk_add_f32 v[116:117], s[4:5], v[116:117]
	v_pk_add_f32 v[118:119], s[6:7], v[118:119]
	v_pk_add_f32 v[120:121], s[8:9], v[120:121]
	v_add_f32_e32 v115, v116, v117
	v_mov_b32_e32 v122, s21
	v_mov_b32_e32 v123, s23
	v_add_f32_e32 v116, v118, v119
	v_add_f32_e32 v117, v120, v121
	v_fmamk_f32 v115, v115, 0x3a800000, v113
	v_pk_add_f32 v[122:123], s[10:11], v[122:123]
	v_fmamk_f32 v116, v116, 0x3a800000, v113
	v_fmamk_f32 v117, v117, 0x3a800000, v113
	v_mul_f32_e32 v119, 0x4f800000, v115
	v_cmp_gt_f32_e64 s[8:9], s43, v115
	v_add_f32_e32 v118, v122, v123
	v_mul_f32_e32 v120, 0x4f800000, v116
	v_cmp_gt_f32_e32 vcc, s43, v116
	v_mul_f32_e32 v121, 0x4f800000, v117
	v_cmp_gt_f32_e64 s[4:5], s43, v117
	v_cndmask_b32_e64 v115, v115, v119, s[8:9]
	v_fmamk_f32 v118, v118, 0x3a800000, v113
	v_cndmask_b32_e32 v116, v116, v120, vcc
	v_cndmask_b32_e64 v117, v117, v121, s[4:5]
	v_sqrt_f32_e32 v119, v115
	v_mul_f32_e32 v122, 0x4f800000, v118
	v_cmp_gt_f32_e64 s[6:7], s43, v118
	v_sqrt_f32_e32 v120, v116
	v_sqrt_f32_e32 v121, v117
	v_cndmask_b32_e64 v118, v118, v122, s[6:7]
	v_sqrt_f32_e32 v122, v118
	v_add_u32_e32 v123, -1, v119
	v_add_u32_e32 v124, 1, v119
	v_add_u32_e32 v125, -1, v120
	v_add_u32_e32 v127, -1, v121
	v_fma_f32 v131, -v123, v119, v115
	v_add_u32_e32 v126, 1, v120
	v_add_u32_e32 v128, 1, v121
	v_fma_f32 v132, -v124, v119, v115
	v_fma_f32 v133, -v125, v120, v116
	v_fma_f32 v135, -v127, v121, v117
	v_cmp_ge_f32_e64 s[10:11], 0, v131
	v_add_u32_e32 v129, -1, v122
	v_fma_f32 v134, -v126, v120, v116
	v_fma_f32 v136, -v128, v121, v117
	v_cndmask_b32_e64 v119, v119, v123, s[10:11]
	v_cmp_ge_f32_e64 s[10:11], 0, v133
	v_cmp_ge_f32_e64 s[12:13], 0, v135
	v_cmp_lt_f32_e64 s[16:17], 0, v132
	v_add_u32_e32 v130, 1, v122
	v_fma_f32 v137, -v129, v122, v118
	v_cndmask_b32_e64 v120, v120, v125, s[10:11]
	v_cmp_lt_f32_e64 s[10:11], 0, v134
; __device__ __forceinline__ void norm_mod_bf16_phase(const Ctx& F, const bf16_t* xin, const float* gain, const float* shift, const float* scale) {
;     ...
;             for (int u = 0; u < 4; ++u) { const float rstd = 1.0f / sqrtf(s[u] * (1.0f / D) + 1e-6f);
; #pragma unroll
;                 for (int j = 0; j < 2; ++j) { float f[8]; unpack8(raw[u][j], f); float o[8];
; #pragma unroll
;                     for (int e = 0; e < 8; ++e) o[e] = f[e] * rstd * ga[j][e] + sh[j][e];
	v_cndmask_b32_e64 v121, v121, v127, s[12:13]
	v_cmp_lt_f32_e64 s[12:13], 0, v136
	v_cndmask_b32_e64 v119, v119, v124, s[16:17]
	v_fma_f32 v138, -v130, v122, v118
	v_cmp_ge_f32_e64 s[14:15], 0, v137
	v_cndmask_b32_e64 v120, v120, v126, s[10:11]
	v_cndmask_b32_e64 v121, v121, v128, s[12:13]
	v_mul_f32_e32 v123, 0x37800000, v119
	v_cndmask_b32_e64 v122, v122, v129, s[14:15]
	v_cmp_lt_f32_e64 s[14:15], 0, v138
	v_mul_f32_e32 v124, 0x37800000, v120
	v_mul_f32_e32 v125, 0x37800000, v121
	v_cndmask_b32_e64 v119, v119, v123, s[8:9]
	v_cmp_class_f32_e64 s[8:9], v115, v114
	v_cndmask_b32_e64 v122, v122, v130, s[14:15]
	v_cndmask_b32_e32 v120, v120, v124, vcc
	v_cmp_class_f32_e32 vcc, v116, v114
	v_cndmask_b32_e64 v121, v121, v125, s[4:5]
	v_cmp_class_f32_e64 s[4:5], v117, v114
	v_cndmask_b32_e64 v115, v119, v115, s[8:9]
	v_mul_f32_e32 v126, 0x37800000, v122
	v_cndmask_b32_e32 v119, v120, v116, vcc
	v_cndmask_b32_e64 v117, v121, v117, s[4:5]
	v_div_scale_f32 v116, s[4:5], v115, v115, 1.0
	v_cndmask_b32_e64 v122, v122, v126, s[6:7]
	v_cmp_class_f32_e64 s[6:7], v118, v114
	v_div_scale_f32 v120, s[4:5], v119, v119, 1.0
	v_rcp_f32_e32 v127, v116
	v_cndmask_b32_e64 v124, v122, v118, s[6:7]
	v_div_scale_f32 v122, s[6:7], v117, v117, 1.0
	v_rcp_f32_e32 v128, v120
	v_div_scale_f32 v125, s[8:9], v124, v124, 1.0
	v_rcp_f32_e32 v129, v122
	v_rcp_f32_e32 v130, v125
	v_fma_f32 v131, -v116, v127, 1.0
	v_div_scale_f32 v118, vcc, 1.0, v115, 1.0
	v_fma_f32 v132, -v120, v128, 1.0
	v_fmac_f32_e32 v127, v131, v127
	v_div_scale_f32 v121, s[4:5], 1.0, v119, 1.0
	v_fma_f32 v133, -v122, v129, 1.0
	v_fmac_f32_e32 v128, v132, v128
	v_mul_f32_e32 v131, v118, v127
	v_div_scale_f32 v123, s[6:7], 1.0, v117, 1.0
	v_fma_f32 v134, -v125, v130, 1.0
	v_fmac_f32_e32 v129, v133, v129
	v_mul_f32_e32 v132, v121, v128
	v_fma_f32 v135, -v116, v131, v118
	v_div_scale_f32 v126, s[8:9], 1.0, v124, 1.0
	v_fmac_f32_e32 v130, v134, v130
	v_mul_f32_e32 v133, v123, v129
	v_fma_f32 v136, -v120, v132, v121
	v_fmac_f32_e32 v131, v135, v127
	v_mul_f32_e32 v134, v126, v130
	v_fma_f32 v137, -v122, v133, v123
	v_fmac_f32_e32 v132, v136, v128
	v_fma_f32 v116, -v116, v131, v118
	v_fma_f32 v138, -v125, v134, v126
	v_fmac_f32_e32 v133, v137, v129
	v_fma_f32 v118, -v120, v132, v121
	v_div_fmas_f32 v116, v116, v127, v131
	s_mov_b64 vcc, s[4:5]
	v_fmac_f32_e32 v134, v138, v130
	v_fma_f32 v120, -v122, v133, v123
	v_div_fixup_f32 v116, v116, v115, 1.0
	v_div_fmas_f32 v115, v118, v128, v132
	s_mov_b64 vcc, s[6:7]
	v_fma_f32 v125, -v125, v134, v126
	v_pk_mul_f32 v[110:111], v[116:117], v[110:111] op_sel_hi:[0,1]
	v_pk_mul_f32 v[106:107], v[116:117], v[106:107] op_sel_hi:[0,1]
	v_pk_mul_f32 v[104:105], v[116:117], v[104:105] op_sel_hi:[0,1]
	v_pk_mul_f32 v[102:103], v[116:117], v[102:103] op_sel_hi:[0,1]
	v_pk_mul_f32 v[108:109], v[116:117], v[108:109] op_sel_hi:[0,1]
	v_pk_mul_f32 v[78:79], v[116:117], v[78:79] op_sel_hi:[0,1]
	v_pk_mul_f32 v[80:81], v[116:117], v[80:81] op_sel_hi:[0,1]
	v_pk_mul_f32 v[82:83], v[116:117], v[82:83] op_sel_hi:[0,1]
	v_div_fixup_f32 v116, v115, v119, 1.0
	v_div_fmas_f32 v115, v120, v129, v133
	s_mov_b64 vcc, s[8:9]
	v_pk_fma_f32 v[110:111], v[24:25], v[110:111], v[0:1]
	v_pk_fma_f32 v[106:107], v[26:27], v[106:107], v[2:3]
	v_pk_fma_f32 v[104:105], v[28:29], v[104:105], v[4:5]
	v_pk_fma_f32 v[102:103], v[30:31], v[102:103], v[6:7]
	v_pk_fma_f32 v[108:109], v[32:33], v[108:109], v[8:9]
	v_pk_fma_f32 v[118:119], v[34:35], v[78:79], v[10:11] op_sel:[0,1,0] op_sel_hi:[1,0,1]
	v_pk_fma_f32 v[80:81], v[36:37], v[80:81], v[12:13] op_sel:[0,1,0] op_sel_hi:[1,0,1]
	v_pk_fma_f32 v[82:83], v[38:39], v[82:83], v[14:15] op_sel:[0,1,0] op_sel_hi:[1,0,1]
	v_pk_mul_f32 v[100:101], v[116:117], v[100:101] op_sel_hi:[0,1]
	v_pk_mul_f32 v[96:97], v[116:117], v[96:97] op_sel_hi:[0,1]
	v_pk_mul_f32 v[94:95], v[116:117], v[94:95] op_sel_hi:[0,1]
	v_pk_mul_f32 v[92:93], v[116:117], v[92:93] op_sel_hi:[0,1]
	v_pk_mul_f32 v[98:99], v[116:117], v[98:99] op_sel_hi:[0,1]
	v_pk_mul_f32 v[120:121], v[116:117], v[64:65] op_sel_hi:[0,1]
	v_pk_mul_f32 v[122:123], v[116:117], v[66:67] op_sel_hi:[0,1]
	v_pk_mul_f32 v[70:71], v[116:117], v[70:71] op_sel_hi:[0,1]
	v_div_fixup_f32 v116, v115, v117, 1.0
	v_div_fmas_f32 v115, v125, v130, v134
; __device__ __forceinline__ unsigned pk2(float lo, float hi) { f32x2 v = {lo, hi}; bf16x2_t b = __builtin_convertvector(v, bf16x2_t); return __builtin_bit_cast(unsigned, b); }
; __device__ __forceinline__ void norm_mod_bf16_phase(const Ctx& F, const bf16_t* xin, const float* gain, const float* shift, const float* scale) {
;     ...
;     for (int ch = gw; ch < T / 32; ch += NGW) {
;         const int row0 = ch * 32, b = row0 / S;
;         float ga[2][8], sh[2][8];
; #pragma unroll
;         for (int j = 0; j < 2; ++j)
; #pragma unroll
;             for (int h = 0; h < 2; ++h) { const int c = 8 * ln + 512 * j + 4 * h; const f32x4 g = *(const f32x4*)(gain + c), sc = *(const f32x4*)(scale + (size_t)b * 6144 + c), s4 = *(const f32x4*)(shift + (size_t)b * 6144 + c);
; #pragma unroll
;                 for (int e = 0; e < 4; ++e) { ga[j][4 * h + e] = g[e] * (sc[e] + 1.0f); sh[j][4 * h + e] = s4[e]; } }
;         for (int r = 0; r < 32; r += 4) {
;     ...
;                 for (int j = 0; j < 2; ++j) { float f[8]; unpack8(raw[u][j], f); float o[8];
; #pragma unroll
;                     for (int e = 0; e < 8; ++e) o[e] = f[e] * rstd * ga[j][e] + sh[j][e];
;                     u32x4 w; w.x = pk2(o[0], o[1]); w.y = pk2(o[2], o[3]); w.z = pk2(o[4], o[5]); w.w = pk2(o[6], o[7]);
;                     *(u32x4*)(hb + (size_t)(row0 + r + u) * D + 8 * ln + 512 * j) = w; } }
	v_cvt_pk_bf16_f32 v64, v110, v111
	v_cvt_pk_bf16_f32 v65, v106, v107
	v_cvt_pk_bf16_f32 v66, v104, v105
	v_cvt_pk_bf16_f32 v67, v102, v103
	v_cvt_pk_bf16_f32 v78, v108, v109
	v_cvt_pk_bf16_f32 v79, v118, v119
	v_cvt_pk_bf16_f32 v80, v80, v81
	v_cvt_pk_bf16_f32 v81, v82, v83
	v_pk_fma_f32 v[82:83], v[24:25], v[100:101], v[0:1]
	v_pk_fma_f32 v[96:97], v[26:27], v[96:97], v[2:3]
	v_pk_fma_f32 v[94:95], v[28:29], v[94:95], v[4:5]
	v_pk_fma_f32 v[92:93], v[30:31], v[92:93], v[6:7]
	v_pk_fma_f32 v[70:71], v[38:39], v[70:71], v[14:15] op_sel:[0,1,0] op_sel_hi:[1,0,1]
	v_pk_mul_f32 v[90:91], v[116:117], v[90:91] op_sel_hi:[0,1]
	v_pk_mul_f32 v[86:87], v[116:117], v[86:87] op_sel_hi:[0,1]
	v_pk_mul_f32 v[84:85], v[116:117], v[84:85] op_sel_hi:[0,1]
	v_pk_mul_f32 v[76:77], v[116:117], v[76:77] op_sel_hi:[0,1]
	v_pk_mul_f32 v[58:59], v[116:117], v[58:59] op_sel_hi:[0,1]
	v_div_fixup_f32 v108, v115, v124, 1.0
	v_pk_fma_f32 v[98:99], v[32:33], v[98:99], v[8:9]
	v_pk_fma_f32 v[100:101], v[34:35], v[120:121], v[10:11] op_sel:[0,1,0] op_sel_hi:[1,0,1]
	v_pk_fma_f32 v[102:103], v[36:37], v[122:123], v[12:13] op_sel:[0,1,0] op_sel_hi:[1,0,1]
	v_pk_mul_f32 v[88:89], v[116:117], v[88:89] op_sel_hi:[0,1]
	v_pk_mul_f32 v[104:105], v[116:117], v[54:55] op_sel_hi:[0,1]
	v_pk_mul_f32 v[106:107], v[116:117], v[56:57] op_sel_hi:[0,1]
	global_store_dwordx4 v[46:47], v[64:67], off
	global_store_dwordx4 v[46:47], v[78:81], off offset:1024
	v_cvt_pk_bf16_f32 v54, v82, v83
	v_cvt_pk_bf16_f32 v55, v96, v97
	v_cvt_pk_bf16_f32 v56, v94, v95
	v_cvt_pk_bf16_f32 v57, v92, v93
	v_cvt_pk_bf16_f32 v67, v70, v71
	v_pk_fma_f32 v[46:47], v[24:25], v[90:91], v[0:1]
	v_pk_fma_f32 v[70:71], v[26:27], v[86:87], v[2:3]
	v_pk_fma_f32 v[78:79], v[28:29], v[84:85], v[4:5]
	v_pk_fma_f32 v[76:77], v[30:31], v[76:77], v[6:7]
	v_pk_fma_f32 v[58:59], v[38:39], v[58:59], v[14:15] op_sel:[0,1,0] op_sel_hi:[1,0,1]
	v_pk_mul_f32 v[74:75], v[108:109], v[74:75] op_sel_hi:[0,1]
	v_pk_mul_f32 v[68:69], v[108:109], v[68:69] op_sel_hi:[0,1]
	v_pk_mul_f32 v[62:63], v[108:109], v[62:63] op_sel_hi:[0,1]
	v_pk_mul_f32 v[60:61], v[108:109], v[60:61] op_sel_hi:[0,1]
	v_cvt_pk_bf16_f32 v64, v98, v99
	v_cvt_pk_bf16_f32 v65, v100, v101
	v_cvt_pk_bf16_f32 v66, v102, v103
	v_pk_fma_f32 v[80:81], v[32:33], v[88:89], v[8:9]
	v_pk_fma_f32 v[82:83], v[34:35], v[104:105], v[10:11] op_sel:[0,1,0] op_sel_hi:[1,0,1]
	v_pk_fma_f32 v[84:85], v[36:37], v[106:107], v[12:13] op_sel:[0,1,0] op_sel_hi:[1,0,1]
	v_pk_mul_f32 v[72:73], v[108:109], v[72:73] op_sel_hi:[0,1]
	v_pk_mul_f32 v[86:87], v[108:109], v[48:49] op_sel_hi:[0,1]
	v_pk_mul_f32 v[88:89], v[108:109], v[50:51] op_sel_hi:[0,1]
	v_pk_mul_f32 v[52:53], v[108:109], v[52:53] op_sel_hi:[0,1]
	global_store_dwordx4 v[44:45], v[54:57], off
	global_store_dwordx4 v[44:45], v[64:67], off offset:1024
	v_cvt_pk_bf16_f32 v44, v46, v47
	v_cvt_pk_bf16_f32 v45, v70, v71
	v_cvt_pk_bf16_f32 v46, v78, v79
	v_cvt_pk_bf16_f32 v47, v76, v77
	v_cvt_pk_bf16_f32 v51, v58, v59
	v_pk_fma_f32 v[54:55], v[24:25], v[74:75], v[0:1]
	v_pk_fma_f32 v[56:57], v[26:27], v[68:69], v[2:3]
	v_pk_fma_f32 v[58:59], v[28:29], v[62:63], v[4:5]
	v_pk_fma_f32 v[60:61], v[30:31], v[60:61], v[6:7]
	v_cvt_pk_bf16_f32 v48, v80, v81
	v_cvt_pk_bf16_f32 v49, v82, v83
	v_cvt_pk_bf16_f32 v50, v84, v85
	v_pk_fma_f32 v[62:63], v[32:33], v[72:73], v[8:9]
	v_pk_fma_f32 v[64:65], v[34:35], v[86:87], v[10:11] op_sel:[0,1,0] op_sel_hi:[1,0,1]
	v_pk_fma_f32 v[66:67], v[36:37], v[88:89], v[12:13] op_sel:[0,1,0] op_sel_hi:[1,0,1]
	v_pk_fma_f32 v[52:53], v[38:39], v[52:53], v[14:15] op_sel:[0,1,0] op_sel_hi:[1,0,1]
	global_store_dwordx4 v[42:43], v[44:47], off
	global_store_dwordx4 v[42:43], v[48:51], off offset:1024
	v_cvt_pk_bf16_f32 v42, v54, v55
	v_cvt_pk_bf16_f32 v43, v56, v57
	v_cvt_pk_bf16_f32 v44, v58, v59
	v_cvt_pk_bf16_f32 v45, v60, v61
	v_cvt_pk_bf16_f32 v46, v62, v63
	v_cvt_pk_bf16_f32 v47, v64, v65
	v_cvt_pk_bf16_f32 v48, v66, v67
	v_cvt_pk_bf16_f32 v49, v52, v53
	global_store_dwordx4 v[40:41], v[42:45], off
	global_store_dwordx4 v[40:41], v[46:49], off offset:1024
	s_cbranch_scc0 .LBB0_984
	s_add_i32 s0, s0, s1
	s_add_i32 s18, s18, s3
	s_add_i32 s20, s20, s3
	s_add_i32 s22, s22, s3
	s_add_i32 s24, s24, s3
	s_cmpk_gt_i32 s0, 0x7ff
	s_cbranch_scc0 .LBB0_983

; __device__ __forceinline__ void norm_mod_bf16_phase(const Ctx& F, const bf16_t* xin, const float* gain, const float* shift, const float* scale) {
;     ...
;         for (int r = 0; r < 32; r += 4) {
;             u32x4 raw[4][2]; float s[4];
; #pragma unroll
;             for (int u = 0; u < 4; ++u)
; #pragma unroll
;                 for (int j = 0; j < 2; ++j) raw[u][j] = *(const u32x4*)(xin + (size_t)(row0 + r + u) * D + 8 * ln + 512 * j);
; #pragma unroll
;             for (int u = 0; u < 4; ++u) { s[u] = 0.f;
; #pragma unroll
;                 for (int j = 0; j < 2; ++j) { float f[8]; unpack8(raw[u][j], f);
; #pragma unroll
;                     for (int e = 0; e < 8; ++e) s[u] += f[e] * f[e]; }
.LBB0_1204:
	v_lshl_add_u64 v[42:43], s[28:29], 0, v[24:25]
	v_lshl_add_u64 v[44:45], s[36:37], 0, v[24:25]
	v_lshl_add_u64 v[46:47], s[56:57], 0, v[24:25]
	v_lshl_add_u64 v[48:49], s[34:35], 0, v[24:25]
	global_load_dwordx4 v[62:65], v[42:43], off nt
	global_load_dwordx4 v[70:73], v[44:45], off nt
	global_load_dwordx4 v[74:77], v[46:47], off nt
	global_load_dwordx4 v[118:121], v[48:49], off offset:1024 nt
	global_load_dwordx4 v[86:89], v[42:43], off offset:-1024 nt
	global_load_dwordx4 v[90:93], v[44:45], off offset:-1024 nt
	global_load_dwordx4 v[122:125], v[46:47], off offset:-1024 nt
	global_load_dwordx4 v[126:129], v[48:49], off nt
	v_lshl_add_u64 v[50:51], s[26:27], 0, v[24:25]
	v_add_co_u32_e32 v48, vcc, s48, v50
	v_lshl_add_u64 v[52:53], s[30:31], 0, v[24:25]
	s_nop 0
	v_addc_co_u32_e32 v49, vcc, 0, v51, vcc
	v_add_co_u32_e32 v46, vcc, s48, v52
	v_lshl_add_u64 v[54:55], s[38:39], 0, v[24:25]
	s_nop 0
	v_addc_co_u32_e32 v47, vcc, 0, v53, vcc
	v_add_co_u32_e32 v44, vcc, s48, v54
	v_lshl_add_u64 v[56:57], s[40:41], 0, v[24:25]
	s_nop 0
	v_addc_co_u32_e32 v45, vcc, 0, v55, vcc
	v_add_co_u32_e32 v42, vcc, s48, v56
	s_add_u32 s26, s26, 0x2000
	s_nop 0
	v_addc_co_u32_e32 v43, vcc, 0, v57, vcc
	s_addc_u32 s27, s27, 0
	s_add_i32 s19, s19, 4
	s_add_u32 s28, s28, 0x2000
	s_addc_u32 s29, s29, 0
	s_add_u32 s30, s30, 0x2000
	s_addc_u32 s31, s31, 0
	s_add_u32 s34, s34, 0x2000
	s_addc_u32 s35, s35, 0
	s_add_u32 s36, s36, 0x2000
	s_addc_u32 s37, s37, 0
	s_add_u32 s38, s38, 0x2000
	s_addc_u32 s39, s39, 0
	s_add_u32 s40, s40, 0x2000
	s_addc_u32 s41, s41, 0
	s_add_u32 s56, s56, 0x2000
	s_addc_u32 s57, s57, 0
	s_cmp_gt_u32 s19, 27
	s_waitcnt vmcnt(7)
	v_and_b32_e32 v82, 0xffff0000, v64
	s_waitcnt vmcnt(6)
	v_and_b32_e32 v66, 0xffff0000, v71
	s_waitcnt vmcnt(5)
	v_and_b32_e32 v58, 0xffff0000, v76
	v_lshlrev_b32_e32 v59, 16, v76
	s_waitcnt vmcnt(3)
	v_lshlrev_b32_e32 v112, 16, v86
	v_and_b32_e32 v113, 0xffff0000, v86
	v_lshlrev_b32_e32 v108, 16, v87
	v_and_b32_e32 v109, 0xffff0000, v87
	s_waitcnt vmcnt(2)
	v_lshlrev_b32_e32 v94, 16, v93
	v_and_b32_e32 v95, 0xffff0000, v93
	v_lshlrev_b32_e32 v96, 16, v92
	v_and_b32_e32 v97, 0xffff0000, v92
	v_lshlrev_b32_e32 v102, 16, v90
	v_and_b32_e32 v103, 0xffff0000, v90
	s_waitcnt vmcnt(1)
	v_lshlrev_b32_e32 v92, 16, v122
	v_and_b32_e32 v93, 0xffff0000, v122
	v_pk_mul_f32 v[148:149], v[112:113], v[112:113]
	v_and_b32_e32 v60, 0xffff0000, v77
	v_lshlrev_b32_e32 v61, 16, v77
	v_lshlrev_b32_e32 v104, 16, v89
	v_and_b32_e32 v105, 0xffff0000, v89
	v_lshlrev_b32_e32 v106, 16, v88
	v_and_b32_e32 v107, 0xffff0000, v88
	v_lshlrev_b32_e32 v98, 16, v91
	v_and_b32_e32 v99, 0xffff0000, v91
	v_lshlrev_b32_e32 v88, 16, v123
	v_and_b32_e32 v89, 0xffff0000, v123
	s_waitcnt vmcnt(0)
	v_lshlrev_b32_e32 v76, 16, v126
	v_and_b32_e32 v77, 0xffff0000, v126
	v_pk_mul_f32 v[146:147], v[108:109], v[108:109]
	v_pk_mul_f32 v[158:159], v[102:103], v[102:103]
	v_pk_mul_f32 v[168:169], v[92:93], v[92:93]
	v_add_f32_e32 v117, v148, v149
	v_lshlrev_b32_e32 v67, 16, v71
	v_lshlrev_b32_e32 v100, 16, v70
	v_and_b32_e32 v101, 0xffff0000, v70
	v_lshlrev_b32_e32 v70, 16, v127
	v_and_b32_e32 v71, 0xffff0000, v127
	v_pk_mul_f32 v[156:157], v[98:99], v[98:99]
	v_pk_mul_f32 v[166:167], v[88:89], v[88:89]
	v_pk_mul_f32 v[178:179], v[76:77], v[76:77]
	v_add_f32_e32 v148, v158, v159
	v_add_f32_e32 v149, v168, v169
	v_add_f32_e32 v117, v146, v117
	v_lshlrev_b32_e32 v86, 16, v124
	v_and_b32_e32 v87, 0xffff0000, v124
	v_pk_mul_f32 v[144:145], v[106:107], v[106:107]
	v_pk_mul_f32 v[176:177], v[70:71], v[70:71]
	v_add_f32_e32 v158, v178, v179
	v_add_f32_e32 v146, v156, v148
	v_add_f32_e32 v148, v166, v149
	v_add_f32_e32 v117, v147, v117
	v_lshlrev_b32_e32 v83, 16, v64
	v_and_b32_e32 v84, 0xffff0000, v65
	v_lshlrev_b32_e32 v85, 16, v65
	v_lshlrev_b32_e32 v64, 16, v128
	v_and_b32_e32 v65, 0xffff0000, v128
	v_pk_mul_f32 v[154:155], v[96:97], v[96:97]
	v_pk_mul_f32 v[164:165], v[86:87], v[86:87]
	v_add_f32_e32 v149, v176, v158
	v_add_f32_e32 v146, v157, v146
	v_add_f32_e32 v147, v167, v148
	v_add_f32_e32 v117, v144, v117
	v_lshlrev_b32_e32 v78, 16, v125
	v_and_b32_e32 v79, 0xffff0000, v125
	v_pk_mul_f32 v[142:143], v[104:105], v[104:105]
	v_pk_mul_f32 v[174:175], v[64:65], v[64:65]
	v_add_f32_e32 v148, v177, v149
	v_add_f32_e32 v144, v154, v146
	v_add_f32_e32 v146, v164, v147
	v_add_f32_e32 v117, v145, v117
	v_and_b32_e32 v80, 0xffff0000, v63
	v_lshlrev_b32_e32 v81, 16, v63
	v_lshlrev_b32_e32 v110, 16, v62
	v_and_b32_e32 v111, 0xffff0000, v62
	v_lshlrev_b32_e32 v62, 16, v129
	v_and_b32_e32 v63, 0xffff0000, v129
	v_pk_mul_f32 v[152:153], v[94:95], v[94:95]
	v_pk_mul_f32 v[162:163], v[78:79], v[78:79]
	v_add_f32_e32 v147, v174, v148
	v_add_f32_e32 v144, v155, v144
	v_add_f32_e32 v145, v165, v146
	v_add_f32_e32 v117, v142, v117
	v_lshlrev_b32_e32 v90, 16, v74
	v_and_b32_e32 v91, 0xffff0000, v74
	v_pk_mul_f32 v[150:151], v[110:111], v[110:111]
	v_pk_mul_f32 v[172:173], v[62:63], v[62:63]
	v_add_f32_e32 v146, v175, v147
	v_add_f32_e32 v142, v152, v144
	v_add_f32_e32 v144, v162, v145
	v_add_f32_e32 v117, v143, v117
	v_and_b32_e32 v56, 0xffff0000, v75
	v_lshlrev_b32_e32 v57, 16, v75
	v_lshlrev_b32_e32 v74, 16, v118
	v_and_b32_e32 v75, 0xffff0000, v118
	v_pk_mul_f32 v[160:161], v[100:101], v[100:101]
	v_pk_mul_f32 v[170:171], v[90:91], v[90:91]
	v_add_f32_e32 v145, v172, v146
	v_add_f32_e32 v142, v153, v142
	v_add_f32_e32 v143, v163, v144
	v_add_f32_e32 v117, v150, v117
	v_and_b32_e32 v50, 0xffff0000, v119
	v_lshlrev_b32_e32 v51, 16, v119
	v_pk_mul_f32 v[118:119], v[80:81], v[80:81]
	v_pk_mul_f32 v[180:181], v[74:75], v[74:75]
	v_add_f32_e32 v144, v173, v145
; __device__ __forceinline__ float wave_sum_fast(float x) { x = reduce16(x); return (rl_(x, 0) + rl_(x, 16)) + (rl_(x, 32) + rl_(x, 48)); }
; __device__ __forceinline__ void norm_mod_bf16_phase(const Ctx& F, const bf16_t* xin, const float* gain, const float* shift, const float* scale) {
;     ...
;             for (int u = 0; u < 4; ++u) { s[u] = 0.f;
; #pragma unroll
;                 for (int j = 0; j < 2; ++j) { float f[8]; unpack8(raw[u][j], f);
; #pragma unroll
;                     for (int e = 0; e < 8; ++e) s[u] += f[e] * f[e]; }
;                 s[u] = wave_sum_fast(s[u]); }
; #pragma unroll
;             for (int u = 0; u < 4; ++u) { const float rstd = 1.0f / sqrtf(s[u] * (1.0f / D) + 1e-6f);
	v_add_f32_e32 v142, v160, v142
	v_add_f32_e32 v143, v170, v143
	v_add_f32_e32 v117, v151, v117
	v_pk_mul_f32 v[124:125], v[66:67], v[66:67]
	v_pk_mul_f32 v[130:131], v[56:57], v[56:57]
	v_add_f32_e32 v144, v180, v144
	v_add_f32_e32 v142, v161, v142
	v_add_f32_e32 v143, v171, v143
	v_add_f32_e32 v117, v119, v117
	v_and_b32_e32 v68, 0xffff0000, v72
	v_lshlrev_b32_e32 v69, 16, v72
	v_and_b32_e32 v52, 0xffff0000, v120
	v_lshlrev_b32_e32 v53, 16, v120
	v_and_b32_e32 v54, 0xffff0000, v121
	v_lshlrev_b32_e32 v55, 16, v121
	v_pk_mul_f32 v[120:121], v[82:83], v[82:83]
	v_pk_mul_f32 v[136:137], v[50:51], v[50:51]
	v_add_f32_e32 v144, v181, v144
	v_add_f32_e32 v119, v125, v142
	v_add_f32_e32 v125, v131, v143
	v_add_f32_e32 v117, v118, v117
	v_pk_mul_f32 v[126:127], v[68:69], v[68:69]
	v_pk_mul_f32 v[132:133], v[58:59], v[58:59]
	v_add_f32_e32 v131, v137, v144
	v_add_f32_e32 v118, v124, v119
	v_add_f32_e32 v119, v130, v125
	v_add_f32_e32 v117, v121, v117
	v_and_b32_e32 v72, 0xffff0000, v73
	v_lshlrev_b32_e32 v73, 16, v73
	v_pk_mul_f32 v[122:123], v[84:85], v[84:85]
	v_pk_mul_f32 v[138:139], v[52:53], v[52:53]
	v_add_f32_e32 v124, v136, v131
	v_add_f32_e32 v118, v127, v118
	v_add_f32_e32 v119, v133, v119
	v_add_f32_e32 v117, v120, v117
	v_pk_mul_f32 v[128:129], v[72:73], v[72:73]
	v_pk_mul_f32 v[134:135], v[60:61], v[60:61]
	v_add_f32_e32 v121, v139, v124
	v_add_f32_e32 v118, v126, v118
	v_add_f32_e32 v119, v132, v119
	v_add_f32_e32 v117, v123, v117
	v_pk_mul_f32 v[140:141], v[54:55], v[54:55]
	v_add_f32_e32 v120, v138, v121
	v_add_f32_e32 v118, v129, v118
	v_add_f32_e32 v119, v135, v119
	v_add_f32_e32 v117, v122, v117
	v_add_f32_e32 v120, v141, v120
	v_add_f32_e32 v118, v128, v118
	v_add_f32_e32 v119, v134, v119
	v_add_f32_dpp v117, v117, v117 quad_perm:[1,0,3,2] row_mask:0xf bank_mask:0xf bound_ctrl:1
	v_add_f32_e32 v120, v140, v120
	v_add_f32_dpp v118, v118, v118 quad_perm:[1,0,3,2] row_mask:0xf bank_mask:0xf bound_ctrl:1
	v_add_f32_dpp v119, v119, v119 quad_perm:[1,0,3,2] row_mask:0xf bank_mask:0xf bound_ctrl:1
	v_add_f32_dpp v117, v117, v117 quad_perm:[2,3,0,1] row_mask:0xf bank_mask:0xf bound_ctrl:1
	v_add_f32_dpp v120, v120, v120 quad_perm:[1,0,3,2] row_mask:0xf bank_mask:0xf bound_ctrl:1
	v_add_f32_dpp v118, v118, v118 quad_perm:[2,3,0,1] row_mask:0xf bank_mask:0xf bound_ctrl:1
	v_add_f32_dpp v119, v119, v119 quad_perm:[2,3,0,1] row_mask:0xf bank_mask:0xf bound_ctrl:1
	v_add_f32_dpp v117, v117, v117 row_half_mirror row_mask:0xf bank_mask:0xf bound_ctrl:1
	v_add_f32_dpp v120, v120, v120 quad_perm:[2,3,0,1] row_mask:0xf bank_mask:0xf bound_ctrl:1
	v_add_f32_dpp v118, v118, v118 row_half_mirror row_mask:0xf bank_mask:0xf bound_ctrl:1
	v_add_f32_dpp v119, v119, v119 row_half_mirror row_mask:0xf bank_mask:0xf bound_ctrl:1
	v_add_f32_dpp v117, v117, v117 row_mirror row_mask:0xf bank_mask:0xf bound_ctrl:1
	v_add_f32_dpp v120, v120, v120 row_half_mirror row_mask:0xf bank_mask:0xf bound_ctrl:1
	v_add_f32_dpp v118, v118, v118 row_mirror row_mask:0xf bank_mask:0xf bound_ctrl:1
	v_add_f32_dpp v119, v119, v119 row_mirror row_mask:0xf bank_mask:0xf bound_ctrl:1
	v_readlane_b32 s12, v117, 16
	v_readlane_b32 s13, v117, 48
	v_add_f32_dpp v120, v120, v120 row_mirror row_mask:0xf bank_mask:0xf bound_ctrl:1
	v_readlane_b32 s4, v117, 0
	v_readlane_b32 s5, v117, 32
	v_readlane_b32 s6, v118, 0
	v_readlane_b32 s14, v118, 16
	v_readlane_b32 s7, v118, 32
	v_readlane_b32 s15, v118, 48
	v_readlane_b32 s8, v119, 0
	v_readlane_b32 s16, v119, 16
	v_readlane_b32 s9, v119, 32
	v_readlane_b32 s17, v119, 48
	v_mov_b32_e32 v118, s12
	v_mov_b32_e32 v119, s13
	v_readlane_b32 s10, v120, 0
	v_readlane_b32 s21, v120, 16
	v_readlane_b32 s11, v120, 32
	v_readlane_b32 s23, v120, 48
	v_mov_b32_e32 v120, s14
	v_mov_b32_e32 v121, s15
	v_mov_b32_e32 v122, s16
	v_mov_b32_e32 v123, s17
	v_pk_add_f32 v[118:119], s[4:5], v[118:119]
	v_pk_add_f32 v[120:121], s[6:7], v[120:121]
	v_pk_add_f32 v[122:123], s[8:9], v[122:123]
	v_add_f32_e32 v117, v118, v119
	v_mov_b32_e32 v124, s21
	v_mov_b32_e32 v125, s23
	v_add_f32_e32 v118, v120, v121
	v_add_f32_e32 v119, v122, v123
	v_fmamk_f32 v117, v117, 0x3a800000, v115
	v_pk_add_f32 v[124:125], s[10:11], v[124:125]
	v_fmamk_f32 v118, v118, 0x3a800000, v115
	v_fmamk_f32 v119, v119, 0x3a800000, v115
	v_mul_f32_e32 v121, 0x4f800000, v117
	v_cmp_gt_f32_e64 s[8:9], s43, v117
	v_add_f32_e32 v120, v124, v125
	v_mul_f32_e32 v122, 0x4f800000, v118
	v_cmp_gt_f32_e32 vcc, s43, v118
	v_mul_f32_e32 v123, 0x4f800000, v119
	v_cmp_gt_f32_e64 s[4:5], s43, v119
	v_cndmask_b32_e64 v117, v117, v121, s[8:9]
	v_fmamk_f32 v120, v120, 0x3a800000, v115
	v_cndmask_b32_e32 v118, v118, v122, vcc
	v_cndmask_b32_e64 v119, v119, v123, s[4:5]
	v_sqrt_f32_e32 v121, v117
	v_mul_f32_e32 v124, 0x4f800000, v120
	v_cmp_gt_f32_e64 s[6:7], s43, v120
	v_sqrt_f32_e32 v122, v118
	v_sqrt_f32_e32 v123, v119
	v_cndmask_b32_e64 v120, v120, v124, s[6:7]
	v_sqrt_f32_e32 v124, v120
	v_add_u32_e32 v125, -1, v121
	v_add_u32_e32 v126, 1, v121
	v_add_u32_e32 v127, -1, v122
	v_add_u32_e32 v129, -1, v123
	v_fma_f32 v133, -v125, v121, v117
	v_add_u32_e32 v128, 1, v122
	v_add_u32_e32 v130, 1, v123
	v_fma_f32 v134, -v126, v121, v117
	v_fma_f32 v135, -v127, v122, v118
	v_fma_f32 v137, -v129, v123, v119
	v_cmp_ge_f32_e64 s[10:11], 0, v133
	v_add_u32_e32 v131, -1, v124
	v_fma_f32 v136, -v128, v122, v118
	v_fma_f32 v138, -v130, v123, v119
	v_cndmask_b32_e64 v121, v121, v125, s[10:11]
	v_cmp_ge_f32_e64 s[10:11], 0, v135
	v_cmp_ge_f32_e64 s[12:13], 0, v137
	v_cmp_lt_f32_e64 s[16:17], 0, v134
	v_add_u32_e32 v132, 1, v124
	v_fma_f32 v139, -v131, v124, v120
	v_cndmask_b32_e64 v122, v122, v127, s[10:11]
; __device__ __forceinline__ void norm_mod_bf16_phase(const Ctx& F, const bf16_t* xin, const float* gain, const float* shift, const float* scale) {
;     ...
;             for (int u = 0; u < 4; ++u) { const float rstd = 1.0f / sqrtf(s[u] * (1.0f / D) + 1e-6f);
; #pragma unroll
;                 for (int j = 0; j < 2; ++j) { float f[8]; unpack8(raw[u][j], f); float o[8];
; #pragma unroll
;                     for (int e = 0; e < 8; ++e) o[e] = f[e] * rstd * ga[j][e] + sh[j][e];
	v_cmp_lt_f32_e64 s[10:11], 0, v136
	v_cndmask_b32_e64 v123, v123, v129, s[12:13]
	v_cmp_lt_f32_e64 s[12:13], 0, v138
	v_cndmask_b32_e64 v121, v121, v126, s[16:17]
	v_fma_f32 v140, -v132, v124, v120
	v_cmp_ge_f32_e64 s[14:15], 0, v139
	v_cndmask_b32_e64 v122, v122, v128, s[10:11]
	v_cndmask_b32_e64 v123, v123, v130, s[12:13]
	v_mul_f32_e32 v125, 0x37800000, v121
	v_cndmask_b32_e64 v124, v124, v131, s[14:15]
	v_cmp_lt_f32_e64 s[14:15], 0, v140
	v_mul_f32_e32 v126, 0x37800000, v122
	v_mul_f32_e32 v127, 0x37800000, v123
	v_cndmask_b32_e64 v121, v121, v125, s[8:9]
	v_cmp_class_f32_e64 s[8:9], v117, v116
	v_cndmask_b32_e64 v124, v124, v132, s[14:15]
	v_cndmask_b32_e32 v122, v122, v126, vcc
	v_cmp_class_f32_e32 vcc, v118, v116
	v_cndmask_b32_e64 v123, v123, v127, s[4:5]
	v_cmp_class_f32_e64 s[4:5], v119, v116
	v_cndmask_b32_e64 v117, v121, v117, s[8:9]
	v_mul_f32_e32 v128, 0x37800000, v124
	v_cndmask_b32_e32 v121, v122, v118, vcc
	v_cndmask_b32_e64 v119, v123, v119, s[4:5]
	v_div_scale_f32 v118, s[4:5], v117, v117, 1.0
	v_cndmask_b32_e64 v124, v124, v128, s[6:7]
	v_cmp_class_f32_e64 s[6:7], v120, v116
	v_div_scale_f32 v122, s[4:5], v121, v121, 1.0
	v_rcp_f32_e32 v129, v118
	v_cndmask_b32_e64 v126, v124, v120, s[6:7]
	v_div_scale_f32 v124, s[6:7], v119, v119, 1.0
	v_rcp_f32_e32 v130, v122
	v_div_scale_f32 v127, s[8:9], v126, v126, 1.0
	v_rcp_f32_e32 v131, v124
	v_rcp_f32_e32 v132, v127
	v_fma_f32 v133, -v118, v129, 1.0
	v_div_scale_f32 v120, vcc, 1.0, v117, 1.0
	v_fma_f32 v134, -v122, v130, 1.0
	v_fmac_f32_e32 v129, v133, v129
	v_div_scale_f32 v123, s[4:5], 1.0, v121, 1.0
	v_fma_f32 v135, -v124, v131, 1.0
	v_fmac_f32_e32 v130, v134, v130
	v_mul_f32_e32 v133, v120, v129
	v_div_scale_f32 v125, s[6:7], 1.0, v119, 1.0
	v_fma_f32 v136, -v127, v132, 1.0
	v_fmac_f32_e32 v131, v135, v131
	v_mul_f32_e32 v134, v123, v130
	v_fma_f32 v137, -v118, v133, v120
	v_div_scale_f32 v128, s[8:9], 1.0, v126, 1.0
	v_fmac_f32_e32 v132, v136, v132
	v_mul_f32_e32 v135, v125, v131
	v_fma_f32 v138, -v122, v134, v123
	v_fmac_f32_e32 v133, v137, v129
	v_mul_f32_e32 v136, v128, v132
	v_fma_f32 v139, -v124, v135, v125
	v_fmac_f32_e32 v134, v138, v130
	v_fma_f32 v118, -v118, v133, v120
	v_fma_f32 v140, -v127, v136, v128
	v_fmac_f32_e32 v135, v139, v131
	v_fma_f32 v120, -v122, v134, v123
	v_div_fmas_f32 v118, v118, v129, v133
	s_mov_b64 vcc, s[4:5]
	v_fmac_f32_e32 v136, v140, v132
	v_fma_f32 v122, -v124, v135, v125
	v_div_fixup_f32 v118, v118, v117, 1.0
	v_div_fmas_f32 v117, v120, v130, v134
	s_mov_b64 vcc, s[6:7]
	v_fma_f32 v127, -v127, v136, v128
	v_pk_mul_f32 v[112:113], v[118:119], v[112:113] op_sel_hi:[0,1]
	v_pk_mul_f32 v[108:109], v[118:119], v[108:109] op_sel_hi:[0,1]
	v_pk_mul_f32 v[106:107], v[118:119], v[106:107] op_sel_hi:[0,1]
	v_pk_mul_f32 v[104:105], v[118:119], v[104:105] op_sel_hi:[0,1]
	v_pk_mul_f32 v[110:111], v[118:119], v[110:111] op_sel_hi:[0,1]
	v_pk_mul_f32 v[80:81], v[118:119], v[80:81] op_sel_hi:[0,1]
	v_pk_mul_f32 v[82:83], v[118:119], v[82:83] op_sel_hi:[0,1]
	v_pk_mul_f32 v[84:85], v[118:119], v[84:85] op_sel_hi:[0,1]
	v_div_fixup_f32 v118, v117, v121, 1.0
	v_div_fmas_f32 v117, v122, v131, v135
	s_mov_b64 vcc, s[8:9]
	v_pk_fma_f32 v[112:113], v[26:27], v[112:113], v[0:1]
	v_pk_fma_f32 v[108:109], v[28:29], v[108:109], v[2:3]
	v_pk_fma_f32 v[106:107], v[30:31], v[106:107], v[4:5]
	v_pk_fma_f32 v[104:105], v[32:33], v[104:105], v[6:7]
	v_pk_fma_f32 v[110:111], v[34:35], v[110:111], v[8:9]
	v_pk_fma_f32 v[120:121], v[36:37], v[80:81], v[10:11] op_sel:[0,1,0] op_sel_hi:[1,0,1]
	v_pk_fma_f32 v[82:83], v[38:39], v[82:83], v[12:13] op_sel:[0,1,0] op_sel_hi:[1,0,1]
	v_pk_fma_f32 v[84:85], v[40:41], v[84:85], v[14:15] op_sel:[0,1,0] op_sel_hi:[1,0,1]
	v_pk_mul_f32 v[102:103], v[118:119], v[102:103] op_sel_hi:[0,1]
	v_pk_mul_f32 v[98:99], v[118:119], v[98:99] op_sel_hi:[0,1]
	v_pk_mul_f32 v[96:97], v[118:119], v[96:97] op_sel_hi:[0,1]
	v_pk_mul_f32 v[94:95], v[118:119], v[94:95] op_sel_hi:[0,1]
	v_pk_mul_f32 v[100:101], v[118:119], v[100:101] op_sel_hi:[0,1]
	v_pk_mul_f32 v[122:123], v[118:119], v[66:67] op_sel_hi:[0,1]
	v_pk_mul_f32 v[124:125], v[118:119], v[68:69] op_sel_hi:[0,1]
	v_pk_mul_f32 v[72:73], v[118:119], v[72:73] op_sel_hi:[0,1]
	v_div_fixup_f32 v118, v117, v119, 1.0
	v_div_fmas_f32 v117, v127, v132, v136
; __device__ __forceinline__ unsigned pk2(float lo, float hi) { f32x2 v = {lo, hi}; bf16x2_t b = __builtin_convertvector(v, bf16x2_t); return __builtin_bit_cast(unsigned, b); }
; __device__ __forceinline__ void norm_mod_bf16_phase(const Ctx& F, const bf16_t* xin, const float* gain, const float* shift, const float* scale) {
;     ...
;     for (int ch = gw; ch < T / 32; ch += NGW) {
;         const int row0 = ch * 32, b = row0 / S;
;         float ga[2][8], sh[2][8];
; #pragma unroll
;         for (int j = 0; j < 2; ++j)
; #pragma unroll
;             for (int h = 0; h < 2; ++h) { const int c = 8 * ln + 512 * j + 4 * h; const f32x4 g = *(const f32x4*)(gain + c), sc = *(const f32x4*)(scale + (size_t)b * 6144 + c), s4 = *(const f32x4*)(shift + (size_t)b * 6144 + c);
; #pragma unroll
;                 for (int e = 0; e < 4; ++e) { ga[j][4 * h + e] = g[e] * (sc[e] + 1.0f); sh[j][4 * h + e] = s4[e]; } }
;         for (int r = 0; r < 32; r += 4) {
;     ...
;                 for (int j = 0; j < 2; ++j) { float f[8]; unpack8(raw[u][j], f); float o[8];
; #pragma unroll
;                     for (int e = 0; e < 8; ++e) o[e] = f[e] * rstd * ga[j][e] + sh[j][e];
;                     u32x4 w; w.x = pk2(o[0], o[1]); w.y = pk2(o[2], o[3]); w.z = pk2(o[4], o[5]); w.w = pk2(o[6], o[7]);
;                     *(u32x4*)(hb + (size_t)(row0 + r + u) * D + 8 * ln + 512 * j) = w; } }
	v_cvt_pk_bf16_f32 v66, v112, v113
	v_cvt_pk_bf16_f32 v67, v108, v109
	v_cvt_pk_bf16_f32 v68, v106, v107
	v_cvt_pk_bf16_f32 v69, v104, v105
	v_cvt_pk_bf16_f32 v80, v110, v111
	v_cvt_pk_bf16_f32 v81, v120, v121
	v_cvt_pk_bf16_f32 v82, v82, v83
	v_cvt_pk_bf16_f32 v83, v84, v85
	v_pk_fma_f32 v[84:85], v[26:27], v[102:103], v[0:1]
	v_pk_fma_f32 v[98:99], v[28:29], v[98:99], v[2:3]
	v_pk_fma_f32 v[96:97], v[30:31], v[96:97], v[4:5]
	v_pk_fma_f32 v[94:95], v[32:33], v[94:95], v[6:7]
	v_pk_fma_f32 v[72:73], v[40:41], v[72:73], v[14:15] op_sel:[0,1,0] op_sel_hi:[1,0,1]
	v_pk_mul_f32 v[92:93], v[118:119], v[92:93] op_sel_hi:[0,1]
	v_pk_mul_f32 v[88:89], v[118:119], v[88:89] op_sel_hi:[0,1]
	v_pk_mul_f32 v[86:87], v[118:119], v[86:87] op_sel_hi:[0,1]
	v_pk_mul_f32 v[78:79], v[118:119], v[78:79] op_sel_hi:[0,1]
	v_pk_mul_f32 v[60:61], v[118:119], v[60:61] op_sel_hi:[0,1]
	v_div_fixup_f32 v110, v117, v126, 1.0
	v_pk_fma_f32 v[100:101], v[34:35], v[100:101], v[8:9]
	v_pk_fma_f32 v[102:103], v[36:37], v[122:123], v[10:11] op_sel:[0,1,0] op_sel_hi:[1,0,1]
	v_pk_fma_f32 v[104:105], v[38:39], v[124:125], v[12:13] op_sel:[0,1,0] op_sel_hi:[1,0,1]
	v_pk_mul_f32 v[90:91], v[118:119], v[90:91] op_sel_hi:[0,1]
	v_pk_mul_f32 v[106:107], v[118:119], v[56:57] op_sel_hi:[0,1]
	v_pk_mul_f32 v[108:109], v[118:119], v[58:59] op_sel_hi:[0,1]
	global_store_dwordx4 v[48:49], v[66:69], off
	global_store_dwordx4 v[48:49], v[80:83], off offset:1024
	v_cvt_pk_bf16_f32 v56, v84, v85
	v_cvt_pk_bf16_f32 v57, v98, v99
	v_cvt_pk_bf16_f32 v58, v96, v97
	v_cvt_pk_bf16_f32 v59, v94, v95
	v_cvt_pk_bf16_f32 v69, v72, v73
	v_pk_fma_f32 v[48:49], v[26:27], v[92:93], v[0:1]
	v_pk_fma_f32 v[72:73], v[28:29], v[88:89], v[2:3]
	v_pk_fma_f32 v[80:81], v[30:31], v[86:87], v[4:5]
	v_pk_fma_f32 v[78:79], v[32:33], v[78:79], v[6:7]
	v_pk_fma_f32 v[60:61], v[40:41], v[60:61], v[14:15] op_sel:[0,1,0] op_sel_hi:[1,0,1]
	v_pk_mul_f32 v[76:77], v[110:111], v[76:77] op_sel_hi:[0,1]
	v_pk_mul_f32 v[70:71], v[110:111], v[70:71] op_sel_hi:[0,1]
	v_pk_mul_f32 v[64:65], v[110:111], v[64:65] op_sel_hi:[0,1]
	v_pk_mul_f32 v[62:63], v[110:111], v[62:63] op_sel_hi:[0,1]
	v_cvt_pk_bf16_f32 v66, v100, v101
	v_cvt_pk_bf16_f32 v67, v102, v103
	v_cvt_pk_bf16_f32 v68, v104, v105
	v_pk_fma_f32 v[82:83], v[34:35], v[90:91], v[8:9]
	v_pk_fma_f32 v[84:85], v[36:37], v[106:107], v[10:11] op_sel:[0,1,0] op_sel_hi:[1,0,1]
	v_pk_fma_f32 v[86:87], v[38:39], v[108:109], v[12:13] op_sel:[0,1,0] op_sel_hi:[1,0,1]
	v_pk_mul_f32 v[74:75], v[110:111], v[74:75] op_sel_hi:[0,1]
	v_pk_mul_f32 v[88:89], v[110:111], v[50:51] op_sel_hi:[0,1]
	v_pk_mul_f32 v[90:91], v[110:111], v[52:53] op_sel_hi:[0,1]
	v_pk_mul_f32 v[54:55], v[110:111], v[54:55] op_sel_hi:[0,1]
	global_store_dwordx4 v[46:47], v[56:59], off
	global_store_dwordx4 v[46:47], v[66:69], off offset:1024
	v_cvt_pk_bf16_f32 v46, v48, v49
	v_cvt_pk_bf16_f32 v47, v72, v73
	v_cvt_pk_bf16_f32 v48, v80, v81
	v_cvt_pk_bf16_f32 v49, v78, v79
	v_cvt_pk_bf16_f32 v53, v60, v61
	v_pk_fma_f32 v[56:57], v[26:27], v[76:77], v[0:1]
	v_pk_fma_f32 v[58:59], v[28:29], v[70:71], v[2:3]
	v_pk_fma_f32 v[60:61], v[30:31], v[64:65], v[4:5]
	v_pk_fma_f32 v[62:63], v[32:33], v[62:63], v[6:7]
	v_cvt_pk_bf16_f32 v50, v82, v83
	v_cvt_pk_bf16_f32 v51, v84, v85
	v_cvt_pk_bf16_f32 v52, v86, v87
	v_pk_fma_f32 v[64:65], v[34:35], v[74:75], v[8:9]
	v_pk_fma_f32 v[66:67], v[36:37], v[88:89], v[10:11] op_sel:[0,1,0] op_sel_hi:[1,0,1]
	v_pk_fma_f32 v[68:69], v[38:39], v[90:91], v[12:13] op_sel:[0,1,0] op_sel_hi:[1,0,1]
	v_pk_fma_f32 v[54:55], v[40:41], v[54:55], v[14:15] op_sel:[0,1,0] op_sel_hi:[1,0,1]
	global_store_dwordx4 v[44:45], v[46:49], off
	global_store_dwordx4 v[44:45], v[50:53], off offset:1024
	v_cvt_pk_bf16_f32 v44, v56, v57
	v_cvt_pk_bf16_f32 v45, v58, v59
	v_cvt_pk_bf16_f32 v46, v60, v61
	v_cvt_pk_bf16_f32 v47, v62, v63
	v_cvt_pk_bf16_f32 v48, v64, v65
	v_cvt_pk_bf16_f32 v49, v66, v67
	v_cvt_pk_bf16_f32 v50, v68, v69
	v_cvt_pk_bf16_f32 v51, v54, v55
	global_store_dwordx4 v[42:43], v[44:47], off
	global_store_dwordx4 v[42:43], v[48:51], off offset:1024
	s_cbranch_scc0 .LBB0_1204
	s_add_i32 s0, s0, s1
	s_add_i32 s18, s18, s3
	s_add_i32 s20, s20, s3
	s_add_i32 s22, s22, s3
	s_add_i32 s24, s24, s3
	s_cmpk_gt_i32 s0, 0x7ff
	s_cbranch_scc0 .LBB0_1203
